# layer-0 out-proj residual epilogue (f32 input stream) also generated with 128-byte row pieces; its weight rows permuted in the prologue like the other layers
# baseline (speedup 1.0000x reference)
.LBB0_64:
	s_andn2_saveexec_b64 s[22:23], s[22:23]
	s_cbranch_execz .LBB0_66
	v_add_u32_e32 v15, 0xfffff800, v26
	v_lshrrev_b32_e32 v20, 9, v15
	v_mov_b32_e32 v21, v3
	v_readlane_b32 s76, v246, 26
	v_lshlrev_b64 v[22:23], 22, v[20:21]
	v_readlane_b32 s90, v246, 40
	v_readlane_b32 s91, v246, 41
	v_and_b32_e32 v17, 0x3e0, v33
	v_and_b32_e32 v15, 0x3c0, v32
	v_lshl_add_u64 v[22:23], s[90:91], 0, v[22:23]
	v_and_b32_e32 v24, 0x60, v17
	v_and_b32_e32 v25, 0x80, v17
	v_lshlrev_b32_e32 v24, 1, v24
	v_lshrrev_b32_e32 v25, 2, v25
	v_or_b32_e32 v24, v24, v25
	v_and_b32_e32 v25, 0xffffff1f, v17
	v_or_b32_e32 v24, v24, v25
	v_lshlrev_b32_e32 v24, 2, v24
	v_mov_b32_e32 v25, v3
	v_or_b32_e32 v19, v15, v27
	v_lshl_add_u64 v[22:23], v[22:23], 0, v[24:25]
	v_lshl_add_u64 v[22:23], v[22:23], 0, v[2:3]
	v_lshlrev_b32_e32 v24, 12, v19
	v_lshl_add_u64 v[22:23], v[22:23], 0, v[24:25]
	v_add_co_u32_e32 v24, vcc, s38, v22
	v_lshlrev_b64 v[20:21], 21, v[20:21]
	s_nop 0
	v_addc_co_u32_e32 v25, vcc, 0, v23, vcc
	v_add_co_u32_e32 v46, vcc, s39, v22
	v_lshl_add_u64 v[20:21], s[14:15], 0, v[20:21]
	s_nop 0
	v_addc_co_u32_e32 v47, vcc, 0, v23, vcc
	v_add_co_u32_e32 v48, vcc, s40, v22
	v_readlane_b32 s77, v246, 27
	s_nop 0
	v_addc_co_u32_e32 v49, vcc, 0, v23, vcc
	v_add_co_u32_e32 v50, vcc, s41, v22
	v_readlane_b32 s78, v246, 28
	s_nop 0
	v_addc_co_u32_e32 v51, vcc, 0, v23, vcc
	v_add_co_u32_e32 v52, vcc, s42, v22
	v_readlane_b32 s79, v246, 29
	s_nop 0
	v_addc_co_u32_e32 v53, vcc, 0, v23, vcc
	v_add_co_u32_e32 v54, vcc, s43, v22
	v_readlane_b32 s80, v246, 30
	s_nop 0
	v_addc_co_u32_e32 v55, vcc, 0, v23, vcc
	v_add_co_u32_e32 v56, vcc, s44, v22
	v_readlane_b32 s81, v246, 31
	s_nop 0
	v_addc_co_u32_e32 v57, vcc, 0, v23, vcc
	global_load_dword v19, v[22:23], off
	global_load_dword v45, v[24:25], off
	global_load_dword v60, v[46:47], off
	global_load_dword v61, v[48:49], off
	global_load_dword v62, v[50:51], off
	global_load_dword v63, v[52:53], off
	global_load_dword v64, v[54:55], off
	global_load_dword v65, v[56:57], off
	v_add_co_u32_e32 v24, vcc, s45, v22
	v_readlane_b32 s82, v246, 32
	s_nop 0
	v_addc_co_u32_e32 v25, vcc, 0, v23, vcc
	v_add_co_u32_e32 v46, vcc, s46, v22
	v_readlane_b32 s83, v246, 33
	s_nop 0
	v_addc_co_u32_e32 v47, vcc, 0, v23, vcc
	v_add_co_u32_e32 v48, vcc, s47, v22
	v_readlane_b32 s84, v246, 34
	s_nop 0
	v_addc_co_u32_e32 v49, vcc, 0, v23, vcc
	v_add_co_u32_e32 v50, vcc, s48, v22
	v_readlane_b32 s85, v246, 35
	s_nop 0
	v_addc_co_u32_e32 v51, vcc, 0, v23, vcc
	v_add_co_u32_e32 v52, vcc, s49, v22
	v_readlane_b32 s86, v246, 36
	s_nop 0
	v_addc_co_u32_e32 v53, vcc, 0, v23, vcc
	v_add_co_u32_e32 v54, vcc, s50, v22
	v_readlane_b32 s87, v246, 37
	s_nop 0
	v_addc_co_u32_e32 v55, vcc, 0, v23, vcc
	v_add_co_u32_e32 v56, vcc, s51, v22
	v_readlane_b32 s88, v246, 38
	s_nop 0
	v_addc_co_u32_e32 v57, vcc, 0, v23, vcc
	v_add_co_u32_e32 v58, vcc, s53, v22
	v_readlane_b32 s89, v246, 39
	s_nop 0
	v_addc_co_u32_e32 v59, vcc, 0, v23, vcc
	global_load_dword v66, v[24:25], off
	global_load_dword v67, v[46:47], off
	global_load_dword v68, v[48:49], off
	global_load_dword v69, v[50:51], off
	global_load_dword v70, v[52:53], off
	global_load_dword v71, v[54:55], off
	global_load_dword v72, v[56:57], off
	global_load_dword v73, v[58:59], off
	v_add_co_u32_e32 v24, vcc, s54, v22
	s_nop 1
	v_addc_co_u32_e32 v25, vcc, 0, v23, vcc
	v_add_co_u32_e32 v46, vcc, s55, v22
	s_nop 1
	v_addc_co_u32_e32 v47, vcc, 0, v23, vcc
	v_add_co_u32_e32 v48, vcc, s56, v22
	s_nop 1
	v_addc_co_u32_e32 v49, vcc, 0, v23, vcc
	v_add_co_u32_e32 v50, vcc, s57, v22
	s_nop 1
	v_addc_co_u32_e32 v51, vcc, 0, v23, vcc
	v_add_co_u32_e32 v52, vcc, s58, v22
	s_nop 1
	v_addc_co_u32_e32 v53, vcc, 0, v23, vcc
	v_add_co_u32_e32 v54, vcc, s59, v22
	s_nop 1
	v_addc_co_u32_e32 v55, vcc, 0, v23, vcc
	v_add_co_u32_e32 v56, vcc, s60, v22
	s_nop 1
	v_addc_co_u32_e32 v57, vcc, 0, v23, vcc
	v_add_co_u32_e32 v58, vcc, s61, v22
	s_nop 1
	v_addc_co_u32_e32 v59, vcc, 0, v23, vcc
	global_load_dword v74, v[24:25], off
	global_load_dword v75, v[46:47], off
	global_load_dword v76, v[48:49], off
	global_load_dword v77, v[50:51], off
	global_load_dword v78, v[52:53], off
	global_load_dword v79, v[54:55], off
	global_load_dword v81, v[56:57], off
	s_nop 0
	global_load_dword v58, v[58:59], off
	v_add_co_u32_e32 v24, vcc, s62, v22
	s_nop 1
	v_addc_co_u32_e32 v25, vcc, 0, v23, vcc
	v_add_co_u32_e32 v46, vcc, s63, v22
	s_nop 1
	v_addc_co_u32_e32 v47, vcc, 0, v23, vcc
	v_add_co_u32_e32 v48, vcc, s64, v22
	s_nop 1
	v_addc_co_u32_e32 v49, vcc, 0, v23, vcc
	v_add_co_u32_e32 v50, vcc, s65, v22
	s_nop 1
	v_addc_co_u32_e32 v51, vcc, 0, v23, vcc
	v_add_co_u32_e32 v52, vcc, s66, v22
	s_nop 1
	v_addc_co_u32_e32 v53, vcc, 0, v23, vcc
	v_add_co_u32_e32 v54, vcc, s67, v22
	s_nop 1
	v_addc_co_u32_e32 v55, vcc, 0, v23, vcc
	v_add_co_u32_e32 v56, vcc, s68, v22
	s_nop 1
	v_addc_co_u32_e32 v57, vcc, 0, v23, vcc
	v_add_co_u32_e32 v22, vcc, s69, v22
	s_nop 1
	v_addc_co_u32_e32 v23, vcc, 0, v23, vcc
	global_load_dword v24, v[24:25], off
	s_nop 0
	global_load_dword v25, v[46:47], off
	s_nop 0
	global_load_dword v46, v[48:49], off
	global_load_dword v47, v[50:51], off
	s_nop 0
	global_load_dword v48, v[52:53], off
	global_load_dword v49, v[54:55], off
	global_load_dword v50, v[56:57], off
	s_nop 0
	global_load_dword v22, v[22:23], off
	s_waitcnt vmcnt(30)
	ds_write2_b32 v34, v19, v45 offset1:66
	s_waitcnt vmcnt(28)
	ds_write2_b32 v34, v60, v61 offset0:132 offset1:198
	s_waitcnt vmcnt(26)
	ds_write2_b32 v35, v62, v63 offset0:8 offset1:74
	s_waitcnt vmcnt(24)
	ds_write2_b32 v35, v64, v65 offset0:140 offset1:206
	s_waitcnt vmcnt(22)
	ds_write2_b32 v36, v66, v67 offset0:16 offset1:82
	s_waitcnt vmcnt(20)
	ds_write2_b32 v36, v68, v69 offset0:148 offset1:214
	s_waitcnt vmcnt(18)
	ds_write2_b32 v37, v70, v71 offset0:24 offset1:90
	s_waitcnt vmcnt(16)
	ds_write2_b32 v37, v72, v73 offset0:156 offset1:222
	s_waitcnt vmcnt(14)
	ds_write2_b32 v38, v74, v75 offset0:32 offset1:98
	s_waitcnt vmcnt(12)
	ds_write2_b32 v38, v76, v77 offset0:164 offset1:230
	s_waitcnt vmcnt(10)
	ds_write2_b32 v39, v78, v79 offset0:40 offset1:106
	s_waitcnt vmcnt(8)
	ds_write2_b32 v39, v81, v58 offset0:172 offset1:238
	s_waitcnt vmcnt(6)
	ds_write2_b32 v40, v24, v25 offset0:48 offset1:114
	s_waitcnt vmcnt(4)
	ds_write2_b32 v40, v46, v47 offset0:180 offset1:246
	s_waitcnt vmcnt(2)
	ds_write2_b32 v41, v48, v49 offset0:56 offset1:122
	s_waitcnt vmcnt(0)
	ds_write2_b32 v41, v50, v22 offset0:188 offset1:254
	s_waitcnt lgkmcnt(0)
	ds_read2_b32 v[24:25], v42 offset1:8
	ds_read2_b32 v[48:49], v42 offset0:33 offset1:41
	ds_read2_b32 v[50:51], v42 offset0:66 offset1:74
	v_lshlrev_b32_e32 v22, 1, v15
	v_mov_b32_e32 v23, v3
	ds_read2_b32 v[52:53], v42 offset0:99 offset1:107
	v_lshl_add_u64 v[20:21], v[20:21], 0, v[22:23]
	v_mov_b32_e32 v19, v3
	s_waitcnt lgkmcnt(3)
	v_bfe_u32 v15, v24, 16, 1
	v_lshl_add_u64 v[46:47], v[20:21], 0, v[18:19]
	v_add3_u32 v15, v24, v15, s70
	s_waitcnt lgkmcnt(2)
	v_bfe_u32 v19, v48, 16, 1
	ds_read2_b32 v[54:55], v42 offset0:132 offset1:140
	v_lshrrev_b32_e32 v15, 16, v15
	v_add3_u32 v19, v48, v19, s70
	ds_read2_b32 v[56:57], v42 offset0:165 offset1:173
	v_and_or_b32 v20, v19, s71, v15
	s_waitcnt lgkmcnt(3)
	v_bfe_u32 v15, v50, 16, 1
	v_add3_u32 v15, v50, v15, s70
	s_waitcnt lgkmcnt(2)
	v_bfe_u32 v19, v52, 16, 1
	ds_read2_b32 v[58:59], v42 offset0:198 offset1:206
	v_lshrrev_b32_e32 v15, 16, v15
	v_add3_u32 v19, v52, v19, s70
	ds_read2_b32 v[60:61], v42 offset0:231 offset1:239
	v_and_or_b32 v21, v19, s71, v15
	s_waitcnt lgkmcnt(3)
	v_bfe_u32 v15, v54, 16, 1
	v_add3_u32 v15, v54, v15, s70
	s_waitcnt lgkmcnt(2)
	v_bfe_u32 v19, v56, 16, 1
	v_lshrrev_b32_e32 v15, 16, v15
	v_add3_u32 v19, v56, v19, s70
	v_and_or_b32 v22, v19, s71, v15
	s_waitcnt lgkmcnt(1)
	v_bfe_u32 v15, v58, 16, 1
	v_add3_u32 v15, v58, v15, s70
	s_waitcnt lgkmcnt(0)
	v_bfe_u32 v19, v60, 16, 1
	v_lshrrev_b32_e32 v15, 16, v15
	v_add3_u32 v19, v60, v19, s70
	v_and_or_b32 v23, v19, s71, v15
	v_or_b32_e32 v15, v17, v28
	v_lshlrev_b32_e32 v62, 11, v15
	v_bfe_u32 v15, v25, 16, 1
	v_mov_b32_e32 v63, v3
	v_add3_u32 v15, v25, v15, s70
	v_bfe_u32 v19, v49, 16, 1
	v_lshl_add_u64 v[62:63], v[46:47], 0, v[62:63]
	v_lshrrev_b32_e32 v15, 16, v15
	v_add3_u32 v19, v49, v19, s70
	global_store_dwordx4 v[62:63], v[20:23], off
	v_mov_b32_e32 v25, v3
	ds_read2_b32 v[48:49], v42 offset0:16 offset1:24
	v_and_or_b32 v20, v19, s71, v15
	v_bfe_u32 v15, v51, 16, 1
	v_add3_u32 v15, v51, v15, s70
	v_bfe_u32 v19, v53, 16, 1
	v_lshrrev_b32_e32 v15, 16, v15
	v_add3_u32 v19, v53, v19, s70
	v_and_or_b32 v21, v19, s71, v15
	v_bfe_u32 v15, v55, 16, 1
	v_add3_u32 v15, v55, v15, s70
	v_bfe_u32 v19, v57, 16, 1
	v_lshrrev_b32_e32 v15, 16, v15
	v_add3_u32 v19, v57, v19, s70
	v_and_or_b32 v22, v19, s71, v15
	v_bfe_u32 v15, v59, 16, 1
	v_add3_u32 v15, v59, v15, s70
	v_bfe_u32 v19, v61, 16, 1
	v_lshrrev_b32_e32 v15, 16, v15
	v_add3_u32 v19, v61, v19, s70
	v_and_or_b32 v23, v19, s71, v15
	v_or_b32_e32 v15, v17, v29
	v_lshlrev_b32_e32 v24, 11, v15
	v_lshl_add_u64 v[24:25], v[46:47], 0, v[24:25]
	global_store_dwordx4 v[24:25], v[20:23], off
	ds_read2_b32 v[24:25], v42 offset0:49 offset1:57
	ds_read2_b32 v[50:51], v42 offset0:82 offset1:90
	ds_read2_b32 v[52:53], v42 offset0:115 offset1:123
	s_waitcnt lgkmcnt(3)
	v_bfe_u32 v15, v48, 16, 1
	v_add3_u32 v15, v48, v15, s70
	s_waitcnt lgkmcnt(2)
	v_bfe_u32 v19, v24, 16, 1
	ds_read2_b32 v[54:55], v42 offset0:148 offset1:156
	v_lshrrev_b32_e32 v15, 16, v15
	v_add3_u32 v19, v24, v19, s70
	ds_read2_b32 v[56:57], v42 offset0:181 offset1:189
	v_and_or_b32 v20, v19, s71, v15
	s_waitcnt lgkmcnt(3)
	v_bfe_u32 v15, v50, 16, 1
	v_add3_u32 v15, v50, v15, s70
	s_waitcnt lgkmcnt(2)
	v_bfe_u32 v19, v52, 16, 1
	ds_read2_b32 v[58:59], v42 offset0:214 offset1:222
	v_lshrrev_b32_e32 v15, 16, v15
	v_add3_u32 v19, v52, v19, s70
	ds_read2_b32 v[60:61], v42 offset0:247 offset1:255
	v_and_or_b32 v21, v19, s71, v15
	s_waitcnt lgkmcnt(3)
	v_bfe_u32 v15, v54, 16, 1
	v_add3_u32 v15, v54, v15, s70
	s_waitcnt lgkmcnt(2)
	v_bfe_u32 v19, v56, 16, 1
	v_lshrrev_b32_e32 v15, 16, v15
	v_add3_u32 v19, v56, v19, s70
	v_and_or_b32 v22, v19, s71, v15
	s_waitcnt lgkmcnt(1)
	v_bfe_u32 v15, v58, 16, 1
	v_add3_u32 v15, v58, v15, s70
	s_waitcnt lgkmcnt(0)
	v_bfe_u32 v19, v60, 16, 1
	v_lshrrev_b32_e32 v15, 16, v15
	v_add3_u32 v19, v60, v19, s70
	v_and_or_b32 v23, v19, s71, v15
	v_or_b32_e32 v15, v17, v30
	v_lshlrev_b32_e32 v62, 11, v15
	v_bfe_u32 v15, v49, 16, 1
	v_mov_b32_e32 v63, v3
	v_add3_u32 v15, v49, v15, s70
	v_bfe_u32 v19, v25, 16, 1
	v_lshl_add_u64 v[62:63], v[46:47], 0, v[62:63]
	v_lshrrev_b32_e32 v15, 16, v15
	v_add3_u32 v19, v25, v19, s70
	global_store_dwordx4 v[62:63], v[20:23], off
	v_mov_b32_e32 v25, v3
	s_nop 0
	v_and_or_b32 v20, v19, s71, v15
	v_bfe_u32 v15, v51, 16, 1
	v_add3_u32 v15, v51, v15, s70
	v_bfe_u32 v19, v53, 16, 1
	v_lshrrev_b32_e32 v15, 16, v15
	v_add3_u32 v19, v53, v19, s70
	v_and_or_b32 v21, v19, s71, v15
	v_bfe_u32 v15, v55, 16, 1
	v_add3_u32 v15, v55, v15, s70
	v_bfe_u32 v19, v57, 16, 1
	v_lshrrev_b32_e32 v15, 16, v15
	v_add3_u32 v19, v57, v19, s70
	v_and_or_b32 v22, v19, s71, v15
	v_bfe_u32 v15, v59, 16, 1
	v_add3_u32 v15, v59, v15, s70
	v_bfe_u32 v19, v61, 16, 1
	v_lshrrev_b32_e32 v15, 16, v15
	v_add3_u32 v19, v61, v19, s70
	v_and_or_b32 v23, v19, s71, v15
	v_or_b32_e32 v15, v17, v31
	v_lshlrev_b32_e32 v24, 11, v15
	v_lshl_add_u64 v[24:25], v[46:47], 0, v[24:25]
	global_store_dwordx4 v[24:25], v[20:23], off
	s_waitcnt lgkmcnt(0)

.LBB0_1229:
	s_ashr_i32 s12, s53, 31
	s_lshr_b32 s12, s12, 29
	s_add_i32 s12, s53, s12
	s_ashr_i32 s12, s12, 3
	s_mul_i32 s25, s12, 0x6000
	s_mul_hi_i32 s23, s12, 0x6000
	v_readlane_b32 s12, v246, 17
	v_readlane_b32 s13, v246, 18
	v_readlane_b32 s30, v246, 7
	v_readlane_b32 s31, v246, 8
	s_add_u32 s80, s40, s25
	s_addc_u32 s81, s41, s23
	s_add_u32 s82, s45, s25
	s_addc_u32 s83, s46, s23
	s_mov_b32 s62, 0xaaaaaaaa
	s_mov_b32 s63, 0xaaaaaaaa
	s_mov_b32 s66, 0x55555555
	s_mov_b32 s67, 0x55555555
	s_mov_b32 s32, 0x0504000c
	s_mov_b32 s61, 0x0504020c
	s_mov_b32 s98, 0x0706030c
	v_mbcnt_lo_u32_b32 v172, -1, 0
	v_mbcnt_hi_u32_b32 v172, -1, v172
	v_and_b32_e32 v172, 1, v172
	v_and_b32_e32 v49, 0x60, v192
	v_add_u32_e32 v49, v49, v192
	v_lshl_or_b32 v49, s4, 8, v49
	v_lshlrev_b32_e32 v28, 2, v49
	v_lshl_add_u32 v49, v172, 5, v49
	v_lshl_add_u32 v48, s53, 8, v190
	v_sub_u32_e32 v48, v48, v172
	v_lshl_add_u32 v48, v48, 10, v49
	v_lshlrev_b32_e32 v49, 1, v48
	v_and_b32_e32 v209, 0x60, v192
	v_add_u32_e32 v209, v209, v192
	v_lshl_or_b32 v209, s4, 8, v209
	v_lshl_add_u32 v29, s53, 8, v190
	v_lshl_add_u32 v209, v29, 10, v209
	v_lshlrev_b32_e32 v209, 2, v209
	global_load_dwordx4 v[174:177], v28, s[80:81] offset:0
	global_load_dwordx4 v[178:181], v28, s[80:81] offset:16
	global_load_dwordx4 v[194:197], v28, s[12:13] offset:0
	global_load_dwordx4 v[210:213], v28, s[12:13] offset:16
	global_load_dwordx4 v[182:185], v28, s[80:81] offset:128
	global_load_dwordx4 v[186:189], v28, s[80:81] offset:144
	global_load_dwordx4 v[214:217], v28, s[12:13] offset:128
	global_load_dwordx4 v[218:221], v28, s[12:13] offset:144
	global_load_dwordx4 v[222:225], v28, s[82:83] offset:0
	global_load_dwordx4 v[226:229], v28, s[82:83] offset:16
	s_waitcnt vmcnt(0)
	v_pk_add_f32 v[222:223], v[222:223], 1.0 op_sel_hi:[1,0]
	v_pk_add_f32 v[224:225], v[224:225], 1.0 op_sel_hi:[1,0]
	v_pk_add_f32 v[226:227], v[226:227], 1.0 op_sel_hi:[1,0]
	v_pk_add_f32 v[228:229], v[228:229], 1.0 op_sel_hi:[1,0]
	v_pk_mul_f32 v[194:195], v[194:195], v[222:223]
	v_pk_mul_f32 v[196:197], v[196:197], v[224:225]
	v_pk_mul_f32 v[210:211], v[210:211], v[226:227]
	v_pk_mul_f32 v[212:213], v[212:213], v[228:229]
	s_nop 1
	global_load_dwordx4 v[222:225], v28, s[82:83] offset:128
	global_load_dwordx4 v[226:229], v28, s[82:83] offset:144
	s_waitcnt vmcnt(0)
	v_pk_add_f32 v[222:223], v[222:223], 1.0 op_sel_hi:[1,0]
	v_pk_add_f32 v[224:225], v[224:225], 1.0 op_sel_hi:[1,0]
	v_pk_add_f32 v[226:227], v[226:227], 1.0 op_sel_hi:[1,0]
	v_pk_add_f32 v[228:229], v[228:229], 1.0 op_sel_hi:[1,0]
	v_pk_mul_f32 v[214:215], v[214:215], v[222:223]
	v_pk_mul_f32 v[216:217], v[216:217], v[224:225]
	v_pk_mul_f32 v[218:219], v[218:219], v[226:227]
	v_pk_mul_f32 v[220:221], v[220:221], v[228:229]
	s_add_u32 s84, s30, 0x0
	s_addc_u32 s85, s31, 0
	global_load_dwordx4 v[222:225], v209, s[84:85] offset:0
	global_load_dwordx4 v[226:229], v209, s[84:85] offset:16
	global_load_dwordx4 v[230:233], v209, s[84:85] offset:128
	global_load_dwordx4 v[234:237], v209, s[84:85] offset:144
	s_waitcnt vmcnt(0)
	v_pk_fma_f32 v[142:143], v[142:143], v[174:175], v[222:223]
	v_pk_fma_f32 v[144:145], v[144:145], v[176:177], v[224:225]
	v_pk_fma_f32 v[138:139], v[138:139], v[178:179], v[226:227]
	v_pk_fma_f32 v[140:141], v[140:141], v[180:181], v[228:229]
	v_pk_fma_f32 v[134:135], v[134:135], v[182:183], v[230:231]
	v_pk_fma_f32 v[136:137], v[136:137], v[184:185], v[232:233]
	v_pk_fma_f32 v[130:131], v[130:131], v[186:187], v[234:235]
	v_pk_fma_f32 v[132:133], v[132:133], v[188:189], v[236:237]
	v_mul_f32_e32 v28, v143, v143
	v_mul_f32_e32 v29, v145, v145
	v_mul_f32_e32 v30, v139, v139
	v_mul_f32_e32 v31, v141, v141
	v_fmac_f32_e32 v28, v142, v142
	v_fmac_f32_e32 v29, v144, v144
	v_fmac_f32_e32 v30, v138, v138
	v_fmac_f32_e32 v31, v140, v140
	v_add_f32_e32 v28, v28, v29
	v_add_f32_e32 v30, v30, v31
	v_add_f32_e32 v173, v28, v30
	v_add_u32_e32 v28, 0x80, v142
	v_add_u32_e32 v29, 0x80, v143
	v_add_u32_e32 v30, 0x80, v144
	v_add_u32_e32 v31, 0x80, v145
	v_perm_b32 v44, v29, v28, s78
	v_perm_b32 v45, v31, v30, s78
	v_perm_b32 v26, v29, v28, s79
	v_perm_b32 v27, v31, v30, s79
	v_perm_b32 v32, v27, v26, s60
	v_add_u32_e32 v28, 0x80, v138
	v_add_u32_e32 v29, 0x80, v139
	v_add_u32_e32 v30, 0x80, v140
	v_add_u32_e32 v31, 0x80, v141
	v_perm_b32 v46, v29, v28, s78
	v_perm_b32 v47, v31, v30, s78
	v_perm_b32 v26, v29, v28, s79
	v_perm_b32 v27, v31, v30, s79
	v_perm_b32 v33, v27, v26, s60
	v_mul_f32_e32 v28, v135, v135
	v_mul_f32_e32 v29, v137, v137
	v_mul_f32_e32 v30, v131, v131
	v_mul_f32_e32 v31, v133, v133
	v_fmac_f32_e32 v28, v134, v134
	v_fmac_f32_e32 v29, v136, v136
	v_fmac_f32_e32 v30, v130, v130
	v_fmac_f32_e32 v31, v132, v132
	v_add_f32_e32 v28, v28, v29
	v_add_f32_e32 v30, v30, v31
	v_add_f32_e32 v28, v28, v30
	v_add_f32_e32 v173, v173, v28
	v_add_u32_e32 v28, 0x80, v134
	v_add_u32_e32 v29, 0x80, v135
	v_add_u32_e32 v30, 0x80, v136
	v_add_u32_e32 v31, 0x80, v137
	v_perm_b32 v168, v29, v28, s78
	v_perm_b32 v169, v31, v30, s78
	v_perm_b32 v26, v29, v28, s79
	v_perm_b32 v27, v31, v30, s79
	v_perm_b32 v42, v27, v26, s60
	v_add_u32_e32 v28, 0x80, v130
	v_add_u32_e32 v29, 0x80, v131
	v_add_u32_e32 v30, 0x80, v132
	v_add_u32_e32 v31, 0x80, v133
	v_perm_b32 v170, v29, v28, s78
	v_perm_b32 v171, v31, v30, s78
	v_perm_b32 v26, v29, v28, s79
	v_perm_b32 v27, v31, v30, s79
	v_perm_b32 v43, v27, v26, s60
	s_mov_b64 vcc, s[66:67]
	v_cndmask_b32_dpp v222, v168, v44, vcc quad_perm:[1,0,3,2] row_mask:0xf bank_mask:0xf
	v_cndmask_b32_dpp v223, v169, v45, vcc quad_perm:[1,0,3,2] row_mask:0xf bank_mask:0xf
	v_cndmask_b32_dpp v224, v170, v46, vcc quad_perm:[1,0,3,2] row_mask:0xf bank_mask:0xf
	v_cndmask_b32_dpp v225, v171, v47, vcc quad_perm:[1,0,3,2] row_mask:0xf bank_mask:0xf
	s_mov_b64 vcc, s[62:63]
	v_cndmask_b32_dpp v168, v44, v168, vcc quad_perm:[1,0,3,2] row_mask:0xf bank_mask:0xf
	v_cndmask_b32_dpp v169, v45, v169, vcc quad_perm:[1,0,3,2] row_mask:0xf bank_mask:0xf
	v_cndmask_b32_dpp v170, v46, v170, vcc quad_perm:[1,0,3,2] row_mask:0xf bank_mask:0xf
	v_cndmask_b32_dpp v171, v47, v171, vcc quad_perm:[1,0,3,2] row_mask:0xf bank_mask:0xf
	s_mov_b64 vcc, s[66:67]
	v_cndmask_b32_dpp v226, v42, v32, vcc quad_perm:[1,0,3,2] row_mask:0xf bank_mask:0xf
	v_cndmask_b32_dpp v227, v43, v33, vcc quad_perm:[1,0,3,2] row_mask:0xf bank_mask:0xf
	s_mov_b64 vcc, s[62:63]
	v_cndmask_b32_dpp v42, v32, v42, vcc quad_perm:[1,0,3,2] row_mask:0xf bank_mask:0xf
	v_cndmask_b32_dpp v43, v33, v43, vcc quad_perm:[1,0,3,2] row_mask:0xf bank_mask:0xf
	s_add_u32 s88, s58, 0x0
	s_addc_u32 s89, s59, 0
	s_add_u32 s90, s74, 0x0
	s_addc_u32 s91, s75, 0
	global_store_dwordx4 v49, v[222:225], s[88:89]
	global_store_dwordx4 v49, v[168:171], s[88:89] offset:2048
	global_store_dwordx2 v48, v[226:227], s[90:91]
	global_store_dwordx2 v48, v[42:43], s[90:91] offset:1024
	s_add_u32 s92, s96, 0x0
	s_addc_u32 s93, s97, 0
	v_pk_mul_f32 v[142:143], v[194:195], v[142:143]
	v_pk_mul_f32 v[144:145], v[196:197], v[144:145]
	v_pk_mul_f32 v[138:139], v[210:211], v[138:139]
	v_pk_mul_f32 v[140:141], v[212:213], v[140:141]
	v_cvt_pk_bf16_f32 v44, v142, v143
	v_cvt_pk_bf16_f32 v45, v144, v145
	v_cvt_pk_bf16_f32 v46, v138, v139
	v_cvt_pk_bf16_f32 v47, v140, v141
	v_pk_mul_f32 v[134:135], v[214:215], v[134:135]
	v_pk_mul_f32 v[136:137], v[216:217], v[136:137]
	v_pk_mul_f32 v[130:131], v[218:219], v[130:131]
	v_pk_mul_f32 v[132:133], v[220:221], v[132:133]
	v_cvt_pk_bf16_f32 v168, v134, v135
	v_cvt_pk_bf16_f32 v169, v136, v137
	v_cvt_pk_bf16_f32 v170, v130, v131
	v_cvt_pk_bf16_f32 v171, v132, v133
	s_mov_b64 vcc, s[66:67]
	v_cndmask_b32_dpp v222, v168, v44, vcc quad_perm:[1,0,3,2] row_mask:0xf bank_mask:0xf
	v_cndmask_b32_dpp v223, v169, v45, vcc quad_perm:[1,0,3,2] row_mask:0xf bank_mask:0xf
	v_cndmask_b32_dpp v224, v170, v46, vcc quad_perm:[1,0,3,2] row_mask:0xf bank_mask:0xf
	v_cndmask_b32_dpp v225, v171, v47, vcc quad_perm:[1,0,3,2] row_mask:0xf bank_mask:0xf
	s_mov_b64 vcc, s[62:63]
	v_cndmask_b32_dpp v168, v44, v168, vcc quad_perm:[1,0,3,2] row_mask:0xf bank_mask:0xf
	v_cndmask_b32_dpp v169, v45, v169, vcc quad_perm:[1,0,3,2] row_mask:0xf bank_mask:0xf
	v_cndmask_b32_dpp v170, v46, v170, vcc quad_perm:[1,0,3,2] row_mask:0xf bank_mask:0xf
	v_cndmask_b32_dpp v171, v47, v171, vcc quad_perm:[1,0,3,2] row_mask:0xf bank_mask:0xf
	global_store_dwordx4 v49, v[222:225], s[92:93]
	global_store_dwordx4 v49, v[168:171], s[92:93] offset:2048
	v_mov_b32_e32 v130, v173
	s_add_u32 s84, s30, 0x10000
	s_addc_u32 s85, s31, 0
	global_load_dwordx4 v[132:135], v209, s[84:85] offset:0
	global_load_dwordx4 v[136:139], v209, s[84:85] offset:16
	global_load_dwordx4 v[140:143], v209, s[84:85] offset:128
	global_load_dwordx4 v[222:225], v209, s[84:85] offset:144
	s_add_u32 s84, s30, 0x20000
	s_addc_u32 s85, s31, 0
	global_load_dwordx4 v[226:229], v209, s[84:85] offset:0
	global_load_dwordx4 v[230:233], v209, s[84:85] offset:16
	global_load_dwordx4 v[234:237], v209, s[84:85] offset:128
	global_load_dwordx4 v[238:241], v209, s[84:85] offset:144
	s_waitcnt vmcnt(4)
	v_pk_fma_f32 v[126:127], v[126:127], v[174:175], v[132:133]
	v_pk_fma_f32 v[128:129], v[128:129], v[176:177], v[134:135]
	v_pk_fma_f32 v[122:123], v[122:123], v[178:179], v[136:137]
	v_pk_fma_f32 v[124:125], v[124:125], v[180:181], v[138:139]
	v_pk_fma_f32 v[118:119], v[118:119], v[182:183], v[140:141]
	v_pk_fma_f32 v[120:121], v[120:121], v[184:185], v[142:143]
	v_pk_fma_f32 v[114:115], v[114:115], v[186:187], v[222:223]
	v_pk_fma_f32 v[116:117], v[116:117], v[188:189], v[224:225]
	v_mul_f32_e32 v28, v127, v127
	v_mul_f32_e32 v29, v129, v129
	v_mul_f32_e32 v30, v123, v123
	v_mul_f32_e32 v31, v125, v125
	v_fmac_f32_e32 v28, v126, v126
	v_fmac_f32_e32 v29, v128, v128
	v_fmac_f32_e32 v30, v122, v122
	v_fmac_f32_e32 v31, v124, v124
	v_add_f32_e32 v28, v28, v29
	v_add_f32_e32 v30, v30, v31
	v_add_f32_e32 v173, v28, v30
	v_add_u32_e32 v28, 0x80, v126
	v_add_u32_e32 v29, 0x80, v127
	v_add_u32_e32 v30, 0x80, v128
	v_add_u32_e32 v31, 0x80, v129
	v_perm_b32 v44, v29, v28, s78
	v_perm_b32 v45, v31, v30, s78
	v_perm_b32 v26, v29, v28, s79
	v_perm_b32 v27, v31, v30, s79
	v_perm_b32 v32, v27, v26, s60
	v_add_u32_e32 v28, 0x80, v122
	v_add_u32_e32 v29, 0x80, v123
	v_add_u32_e32 v30, 0x80, v124
	v_add_u32_e32 v31, 0x80, v125
	v_perm_b32 v46, v29, v28, s78
	v_perm_b32 v47, v31, v30, s78
	v_perm_b32 v26, v29, v28, s79
	v_perm_b32 v27, v31, v30, s79
	v_perm_b32 v33, v27, v26, s60
	v_mul_f32_e32 v28, v119, v119
	v_mul_f32_e32 v29, v121, v121
	v_mul_f32_e32 v30, v115, v115
	v_mul_f32_e32 v31, v117, v117
	v_fmac_f32_e32 v28, v118, v118
	v_fmac_f32_e32 v29, v120, v120
	v_fmac_f32_e32 v30, v114, v114
	v_fmac_f32_e32 v31, v116, v116
	v_add_f32_e32 v28, v28, v29
	v_add_f32_e32 v30, v30, v31
	v_add_f32_e32 v28, v28, v30
	v_add_f32_e32 v173, v173, v28
	v_add_u32_e32 v28, 0x80, v118
	v_add_u32_e32 v29, 0x80, v119
	v_add_u32_e32 v30, 0x80, v120
	v_add_u32_e32 v31, 0x80, v121
	v_perm_b32 v168, v29, v28, s78
	v_perm_b32 v169, v31, v30, s78
	v_perm_b32 v26, v29, v28, s79
	v_perm_b32 v27, v31, v30, s79
	v_perm_b32 v42, v27, v26, s60
	v_add_u32_e32 v28, 0x80, v114
	v_add_u32_e32 v29, 0x80, v115
	v_add_u32_e32 v30, 0x80, v116
	v_add_u32_e32 v31, 0x80, v117
	v_perm_b32 v170, v29, v28, s78
	v_perm_b32 v171, v31, v30, s78
	v_perm_b32 v26, v29, v28, s79
	v_perm_b32 v27, v31, v30, s79
	v_perm_b32 v43, v27, v26, s60
	s_mov_b64 vcc, s[66:67]
	v_cndmask_b32_dpp v132, v168, v44, vcc quad_perm:[1,0,3,2] row_mask:0xf bank_mask:0xf
	v_cndmask_b32_dpp v133, v169, v45, vcc quad_perm:[1,0,3,2] row_mask:0xf bank_mask:0xf
	v_cndmask_b32_dpp v134, v170, v46, vcc quad_perm:[1,0,3,2] row_mask:0xf bank_mask:0xf
	v_cndmask_b32_dpp v135, v171, v47, vcc quad_perm:[1,0,3,2] row_mask:0xf bank_mask:0xf
	s_mov_b64 vcc, s[62:63]
	v_cndmask_b32_dpp v168, v44, v168, vcc quad_perm:[1,0,3,2] row_mask:0xf bank_mask:0xf
	v_cndmask_b32_dpp v169, v45, v169, vcc quad_perm:[1,0,3,2] row_mask:0xf bank_mask:0xf
	v_cndmask_b32_dpp v170, v46, v170, vcc quad_perm:[1,0,3,2] row_mask:0xf bank_mask:0xf
	v_cndmask_b32_dpp v171, v47, v171, vcc quad_perm:[1,0,3,2] row_mask:0xf bank_mask:0xf
	s_mov_b64 vcc, s[66:67]
	v_cndmask_b32_dpp v136, v42, v32, vcc quad_perm:[1,0,3,2] row_mask:0xf bank_mask:0xf
	v_cndmask_b32_dpp v137, v43, v33, vcc quad_perm:[1,0,3,2] row_mask:0xf bank_mask:0xf
	s_mov_b64 vcc, s[62:63]
	v_cndmask_b32_dpp v42, v32, v42, vcc quad_perm:[1,0,3,2] row_mask:0xf bank_mask:0xf
	v_cndmask_b32_dpp v43, v33, v43, vcc quad_perm:[1,0,3,2] row_mask:0xf bank_mask:0xf
	s_add_u32 s88, s58, 0x8000
	s_addc_u32 s89, s59, 0
	s_add_u32 s90, s74, 0x4000
	s_addc_u32 s91, s75, 0
	global_store_dwordx4 v49, v[132:135], s[88:89]
	global_store_dwordx4 v49, v[168:171], s[88:89] offset:2048
	global_store_dwordx2 v48, v[136:137], s[90:91]
	global_store_dwordx2 v48, v[42:43], s[90:91] offset:1024
	s_add_u32 s92, s96, 0x8000
	s_addc_u32 s93, s97, 0
	v_pk_mul_f32 v[126:127], v[194:195], v[126:127]
	v_pk_mul_f32 v[128:129], v[196:197], v[128:129]
	v_pk_mul_f32 v[122:123], v[210:211], v[122:123]
	v_pk_mul_f32 v[124:125], v[212:213], v[124:125]
	v_cvt_pk_bf16_f32 v44, v126, v127
	v_cvt_pk_bf16_f32 v45, v128, v129
	v_cvt_pk_bf16_f32 v46, v122, v123
	v_cvt_pk_bf16_f32 v47, v124, v125
	v_pk_mul_f32 v[118:119], v[214:215], v[118:119]
	v_pk_mul_f32 v[120:121], v[216:217], v[120:121]
	v_pk_mul_f32 v[114:115], v[218:219], v[114:115]
	v_pk_mul_f32 v[116:117], v[220:221], v[116:117]
	v_cvt_pk_bf16_f32 v168, v118, v119
	v_cvt_pk_bf16_f32 v169, v120, v121
	v_cvt_pk_bf16_f32 v170, v114, v115
	v_cvt_pk_bf16_f32 v171, v116, v117
	s_mov_b64 vcc, s[66:67]
	v_cndmask_b32_dpp v132, v168, v44, vcc quad_perm:[1,0,3,2] row_mask:0xf bank_mask:0xf
	v_cndmask_b32_dpp v133, v169, v45, vcc quad_perm:[1,0,3,2] row_mask:0xf bank_mask:0xf
	v_cndmask_b32_dpp v134, v170, v46, vcc quad_perm:[1,0,3,2] row_mask:0xf bank_mask:0xf
	v_cndmask_b32_dpp v135, v171, v47, vcc quad_perm:[1,0,3,2] row_mask:0xf bank_mask:0xf
	s_mov_b64 vcc, s[62:63]
	v_cndmask_b32_dpp v168, v44, v168, vcc quad_perm:[1,0,3,2] row_mask:0xf bank_mask:0xf
	v_cndmask_b32_dpp v169, v45, v169, vcc quad_perm:[1,0,3,2] row_mask:0xf bank_mask:0xf
	v_cndmask_b32_dpp v170, v46, v170, vcc quad_perm:[1,0,3,2] row_mask:0xf bank_mask:0xf
	v_cndmask_b32_dpp v171, v47, v171, vcc quad_perm:[1,0,3,2] row_mask:0xf bank_mask:0xf
	global_store_dwordx4 v49, v[132:135], s[92:93]
	global_store_dwordx4 v49, v[168:171], s[92:93] offset:2048
	v_mov_b32_e32 v114, v173
	s_add_u32 s84, s30, 0x30000
	s_addc_u32 s85, s31, 0
	global_load_dwordx4 v[116:119], v209, s[84:85] offset:0
	global_load_dwordx4 v[120:123], v209, s[84:85] offset:16
	global_load_dwordx4 v[124:127], v209, s[84:85] offset:128
	global_load_dwordx4 v[132:135], v209, s[84:85] offset:144
	s_waitcnt vmcnt(10)
	v_pk_fma_f32 v[110:111], v[110:111], v[174:175], v[226:227]
	v_pk_fma_f32 v[112:113], v[112:113], v[176:177], v[228:229]
	v_pk_fma_f32 v[106:107], v[106:107], v[178:179], v[230:231]
	v_pk_fma_f32 v[108:109], v[108:109], v[180:181], v[232:233]
	v_pk_fma_f32 v[102:103], v[102:103], v[182:183], v[234:235]
	v_pk_fma_f32 v[104:105], v[104:105], v[184:185], v[236:237]
	v_pk_fma_f32 v[98:99], v[98:99], v[186:187], v[238:239]
	v_pk_fma_f32 v[100:101], v[100:101], v[188:189], v[240:241]
	v_mul_f32_e32 v28, v111, v111
	v_mul_f32_e32 v29, v113, v113
	v_mul_f32_e32 v30, v107, v107
	v_mul_f32_e32 v31, v109, v109
	v_fmac_f32_e32 v28, v110, v110
	v_fmac_f32_e32 v29, v112, v112
	v_fmac_f32_e32 v30, v106, v106
	v_fmac_f32_e32 v31, v108, v108
	v_add_f32_e32 v28, v28, v29
	v_add_f32_e32 v30, v30, v31
	v_add_f32_e32 v173, v28, v30
	v_add_u32_e32 v28, 0x80, v110
	v_add_u32_e32 v29, 0x80, v111
	v_add_u32_e32 v30, 0x80, v112
	v_add_u32_e32 v31, 0x80, v113
	v_perm_b32 v44, v29, v28, s78
	v_perm_b32 v45, v31, v30, s78
	v_perm_b32 v26, v29, v28, s79
	v_perm_b32 v27, v31, v30, s79
	v_perm_b32 v32, v27, v26, s60
	v_add_u32_e32 v28, 0x80, v106
	v_add_u32_e32 v29, 0x80, v107
	v_add_u32_e32 v30, 0x80, v108
	v_add_u32_e32 v31, 0x80, v109
	v_perm_b32 v46, v29, v28, s78
	v_perm_b32 v47, v31, v30, s78
	v_perm_b32 v26, v29, v28, s79
	v_perm_b32 v27, v31, v30, s79
	v_perm_b32 v33, v27, v26, s60
	v_mul_f32_e32 v28, v103, v103
	v_mul_f32_e32 v29, v105, v105
	v_mul_f32_e32 v30, v99, v99
	v_mul_f32_e32 v31, v101, v101
	v_fmac_f32_e32 v28, v102, v102
	v_fmac_f32_e32 v29, v104, v104
	v_fmac_f32_e32 v30, v98, v98
	v_fmac_f32_e32 v31, v100, v100
	v_add_f32_e32 v28, v28, v29
	v_add_f32_e32 v30, v30, v31
	v_add_f32_e32 v28, v28, v30
	v_add_f32_e32 v173, v173, v28
	v_add_u32_e32 v28, 0x80, v102
	v_add_u32_e32 v29, 0x80, v103
	v_add_u32_e32 v30, 0x80, v104
	v_add_u32_e32 v31, 0x80, v105
	v_perm_b32 v168, v29, v28, s78
	v_perm_b32 v169, v31, v30, s78
	v_perm_b32 v26, v29, v28, s79
	v_perm_b32 v27, v31, v30, s79
	v_perm_b32 v42, v27, v26, s60
	v_add_u32_e32 v28, 0x80, v98
	v_add_u32_e32 v29, 0x80, v99
	v_add_u32_e32 v30, 0x80, v100
	v_add_u32_e32 v31, 0x80, v101
	v_perm_b32 v170, v29, v28, s78
	v_perm_b32 v171, v31, v30, s78
	v_perm_b32 v26, v29, v28, s79
	v_perm_b32 v27, v31, v30, s79
	v_perm_b32 v43, v27, v26, s60
	s_mov_b64 vcc, s[66:67]
	v_cndmask_b32_dpp v226, v168, v44, vcc quad_perm:[1,0,3,2] row_mask:0xf bank_mask:0xf
	v_cndmask_b32_dpp v227, v169, v45, vcc quad_perm:[1,0,3,2] row_mask:0xf bank_mask:0xf
	v_cndmask_b32_dpp v228, v170, v46, vcc quad_perm:[1,0,3,2] row_mask:0xf bank_mask:0xf
	v_cndmask_b32_dpp v229, v171, v47, vcc quad_perm:[1,0,3,2] row_mask:0xf bank_mask:0xf
	s_mov_b64 vcc, s[62:63]
	v_cndmask_b32_dpp v168, v44, v168, vcc quad_perm:[1,0,3,2] row_mask:0xf bank_mask:0xf
	v_cndmask_b32_dpp v169, v45, v169, vcc quad_perm:[1,0,3,2] row_mask:0xf bank_mask:0xf
	v_cndmask_b32_dpp v170, v46, v170, vcc quad_perm:[1,0,3,2] row_mask:0xf bank_mask:0xf
	v_cndmask_b32_dpp v171, v47, v171, vcc quad_perm:[1,0,3,2] row_mask:0xf bank_mask:0xf
	s_mov_b64 vcc, s[66:67]
	v_cndmask_b32_dpp v230, v42, v32, vcc quad_perm:[1,0,3,2] row_mask:0xf bank_mask:0xf
	v_cndmask_b32_dpp v231, v43, v33, vcc quad_perm:[1,0,3,2] row_mask:0xf bank_mask:0xf
	s_mov_b64 vcc, s[62:63]
	v_cndmask_b32_dpp v42, v32, v42, vcc quad_perm:[1,0,3,2] row_mask:0xf bank_mask:0xf
	v_cndmask_b32_dpp v43, v33, v43, vcc quad_perm:[1,0,3,2] row_mask:0xf bank_mask:0xf
	s_add_u32 s88, s58, 0x10000
	s_addc_u32 s89, s59, 0
	s_add_u32 s90, s74, 0x8000
	s_addc_u32 s91, s75, 0
	global_store_dwordx4 v49, v[226:229], s[88:89]
	global_store_dwordx4 v49, v[168:171], s[88:89] offset:2048
	global_store_dwordx2 v48, v[230:231], s[90:91]
	global_store_dwordx2 v48, v[42:43], s[90:91] offset:1024
	s_add_u32 s92, s96, 0x10000
	s_addc_u32 s93, s97, 0
	v_pk_mul_f32 v[110:111], v[194:195], v[110:111]
	v_pk_mul_f32 v[112:113], v[196:197], v[112:113]
	v_pk_mul_f32 v[106:107], v[210:211], v[106:107]
	v_pk_mul_f32 v[108:109], v[212:213], v[108:109]
	v_cvt_pk_bf16_f32 v44, v110, v111
	v_cvt_pk_bf16_f32 v45, v112, v113
	v_cvt_pk_bf16_f32 v46, v106, v107
	v_cvt_pk_bf16_f32 v47, v108, v109
	v_pk_mul_f32 v[102:103], v[214:215], v[102:103]
	v_pk_mul_f32 v[104:105], v[216:217], v[104:105]
	v_pk_mul_f32 v[98:99], v[218:219], v[98:99]
	v_pk_mul_f32 v[100:101], v[220:221], v[100:101]
	v_cvt_pk_bf16_f32 v168, v102, v103
	v_cvt_pk_bf16_f32 v169, v104, v105
	v_cvt_pk_bf16_f32 v170, v98, v99
	v_cvt_pk_bf16_f32 v171, v100, v101
	s_mov_b64 vcc, s[66:67]
	v_cndmask_b32_dpp v226, v168, v44, vcc quad_perm:[1,0,3,2] row_mask:0xf bank_mask:0xf
	v_cndmask_b32_dpp v227, v169, v45, vcc quad_perm:[1,0,3,2] row_mask:0xf bank_mask:0xf
	v_cndmask_b32_dpp v228, v170, v46, vcc quad_perm:[1,0,3,2] row_mask:0xf bank_mask:0xf
	v_cndmask_b32_dpp v229, v171, v47, vcc quad_perm:[1,0,3,2] row_mask:0xf bank_mask:0xf
	s_mov_b64 vcc, s[62:63]
	v_cndmask_b32_dpp v168, v44, v168, vcc quad_perm:[1,0,3,2] row_mask:0xf bank_mask:0xf
	v_cndmask_b32_dpp v169, v45, v169, vcc quad_perm:[1,0,3,2] row_mask:0xf bank_mask:0xf
	v_cndmask_b32_dpp v170, v46, v170, vcc quad_perm:[1,0,3,2] row_mask:0xf bank_mask:0xf
	v_cndmask_b32_dpp v171, v47, v171, vcc quad_perm:[1,0,3,2] row_mask:0xf bank_mask:0xf
	global_store_dwordx4 v49, v[226:229], s[92:93]
	global_store_dwordx4 v49, v[168:171], s[92:93] offset:2048
	v_mov_b32_e32 v98, v173
	s_add_u32 s84, s30, 0x80000
	s_addc_u32 s85, s31, 0
	global_load_dwordx4 v[100:103], v209, s[84:85] offset:0
	global_load_dwordx4 v[104:107], v209, s[84:85] offset:16
	global_load_dwordx4 v[108:111], v209, s[84:85] offset:128
	global_load_dwordx4 v[136:139], v209, s[84:85] offset:144
	s_waitcnt vmcnt(10)
	v_pk_fma_f32 v[94:95], v[94:95], v[174:175], v[116:117]
	v_pk_fma_f32 v[96:97], v[96:97], v[176:177], v[118:119]
	v_pk_fma_f32 v[90:91], v[90:91], v[178:179], v[120:121]
	v_pk_fma_f32 v[92:93], v[92:93], v[180:181], v[122:123]
	v_pk_fma_f32 v[86:87], v[86:87], v[182:183], v[124:125]
	v_pk_fma_f32 v[88:89], v[88:89], v[184:185], v[126:127]
	v_pk_fma_f32 v[82:83], v[82:83], v[186:187], v[132:133]
	v_pk_fma_f32 v[84:85], v[84:85], v[188:189], v[134:135]
	v_mul_f32_e32 v28, v95, v95
	v_mul_f32_e32 v29, v97, v97
	v_mul_f32_e32 v30, v91, v91
	v_mul_f32_e32 v31, v93, v93
	v_fmac_f32_e32 v28, v94, v94
	v_fmac_f32_e32 v29, v96, v96
	v_fmac_f32_e32 v30, v90, v90
	v_fmac_f32_e32 v31, v92, v92
	v_add_f32_e32 v28, v28, v29
	v_add_f32_e32 v30, v30, v31
	v_add_f32_e32 v173, v28, v30
	v_add_u32_e32 v28, 0x80, v94
	v_add_u32_e32 v29, 0x80, v95
	v_add_u32_e32 v30, 0x80, v96
	v_add_u32_e32 v31, 0x80, v97
	v_perm_b32 v44, v29, v28, s78
	v_perm_b32 v45, v31, v30, s78
	v_perm_b32 v26, v29, v28, s79
	v_perm_b32 v27, v31, v30, s79
	v_perm_b32 v32, v27, v26, s60
	v_add_u32_e32 v28, 0x80, v90
	v_add_u32_e32 v29, 0x80, v91
	v_add_u32_e32 v30, 0x80, v92
	v_add_u32_e32 v31, 0x80, v93
	v_perm_b32 v46, v29, v28, s78
	v_perm_b32 v47, v31, v30, s78
	v_perm_b32 v26, v29, v28, s79
	v_perm_b32 v27, v31, v30, s79
	v_perm_b32 v33, v27, v26, s60
	v_mul_f32_e32 v28, v87, v87
	v_mul_f32_e32 v29, v89, v89
	v_mul_f32_e32 v30, v83, v83
	v_mul_f32_e32 v31, v85, v85
	v_fmac_f32_e32 v28, v86, v86
	v_fmac_f32_e32 v29, v88, v88
	v_fmac_f32_e32 v30, v82, v82
	v_fmac_f32_e32 v31, v84, v84
	v_add_f32_e32 v28, v28, v29
	v_add_f32_e32 v30, v30, v31
	v_add_f32_e32 v28, v28, v30
	v_add_f32_e32 v173, v173, v28
	v_add_u32_e32 v28, 0x80, v86
	v_add_u32_e32 v29, 0x80, v87
	v_add_u32_e32 v30, 0x80, v88
	v_add_u32_e32 v31, 0x80, v89
	v_perm_b32 v168, v29, v28, s78
	v_perm_b32 v169, v31, v30, s78
	v_perm_b32 v26, v29, v28, s79
	v_perm_b32 v27, v31, v30, s79
	v_perm_b32 v42, v27, v26, s60
	v_add_u32_e32 v28, 0x80, v82
	v_add_u32_e32 v29, 0x80, v83
	v_add_u32_e32 v30, 0x80, v84
	v_add_u32_e32 v31, 0x80, v85
	v_perm_b32 v170, v29, v28, s78
	v_perm_b32 v171, v31, v30, s78
	v_perm_b32 v26, v29, v28, s79
	v_perm_b32 v27, v31, v30, s79
	v_perm_b32 v43, v27, v26, s60
	s_mov_b64 vcc, s[66:67]
	v_cndmask_b32_dpp v116, v168, v44, vcc quad_perm:[1,0,3,2] row_mask:0xf bank_mask:0xf
	v_cndmask_b32_dpp v117, v169, v45, vcc quad_perm:[1,0,3,2] row_mask:0xf bank_mask:0xf
	v_cndmask_b32_dpp v118, v170, v46, vcc quad_perm:[1,0,3,2] row_mask:0xf bank_mask:0xf
	v_cndmask_b32_dpp v119, v171, v47, vcc quad_perm:[1,0,3,2] row_mask:0xf bank_mask:0xf
	s_mov_b64 vcc, s[62:63]
	v_cndmask_b32_dpp v168, v44, v168, vcc quad_perm:[1,0,3,2] row_mask:0xf bank_mask:0xf
	v_cndmask_b32_dpp v169, v45, v169, vcc quad_perm:[1,0,3,2] row_mask:0xf bank_mask:0xf
	v_cndmask_b32_dpp v170, v46, v170, vcc quad_perm:[1,0,3,2] row_mask:0xf bank_mask:0xf
	v_cndmask_b32_dpp v171, v47, v171, vcc quad_perm:[1,0,3,2] row_mask:0xf bank_mask:0xf
	s_mov_b64 vcc, s[66:67]
	v_cndmask_b32_dpp v120, v42, v32, vcc quad_perm:[1,0,3,2] row_mask:0xf bank_mask:0xf
	v_cndmask_b32_dpp v121, v43, v33, vcc quad_perm:[1,0,3,2] row_mask:0xf bank_mask:0xf
	s_mov_b64 vcc, s[62:63]
	v_cndmask_b32_dpp v42, v32, v42, vcc quad_perm:[1,0,3,2] row_mask:0xf bank_mask:0xf
	v_cndmask_b32_dpp v43, v33, v43, vcc quad_perm:[1,0,3,2] row_mask:0xf bank_mask:0xf
	s_add_u32 s88, s58, 0x18000
	s_addc_u32 s89, s59, 0
	s_add_u32 s90, s74, 0xc000
	s_addc_u32 s91, s75, 0
	global_store_dwordx4 v49, v[116:119], s[88:89]
	global_store_dwordx4 v49, v[168:171], s[88:89] offset:2048
	global_store_dwordx2 v48, v[120:121], s[90:91]
	global_store_dwordx2 v48, v[42:43], s[90:91] offset:1024
	s_add_u32 s92, s96, 0x18000
	s_addc_u32 s93, s97, 0
	v_pk_mul_f32 v[94:95], v[194:195], v[94:95]
	v_pk_mul_f32 v[96:97], v[196:197], v[96:97]
	v_pk_mul_f32 v[90:91], v[210:211], v[90:91]
	v_pk_mul_f32 v[92:93], v[212:213], v[92:93]
	v_cvt_pk_bf16_f32 v44, v94, v95
	v_cvt_pk_bf16_f32 v45, v96, v97
	v_cvt_pk_bf16_f32 v46, v90, v91
	v_cvt_pk_bf16_f32 v47, v92, v93
	v_pk_mul_f32 v[86:87], v[214:215], v[86:87]
	v_pk_mul_f32 v[88:89], v[216:217], v[88:89]
	v_pk_mul_f32 v[82:83], v[218:219], v[82:83]
	v_pk_mul_f32 v[84:85], v[220:221], v[84:85]
	v_cvt_pk_bf16_f32 v168, v86, v87
	v_cvt_pk_bf16_f32 v169, v88, v89
	v_cvt_pk_bf16_f32 v170, v82, v83
	v_cvt_pk_bf16_f32 v171, v84, v85
	s_mov_b64 vcc, s[66:67]
	v_cndmask_b32_dpp v116, v168, v44, vcc quad_perm:[1,0,3,2] row_mask:0xf bank_mask:0xf
	v_cndmask_b32_dpp v117, v169, v45, vcc quad_perm:[1,0,3,2] row_mask:0xf bank_mask:0xf
	v_cndmask_b32_dpp v118, v170, v46, vcc quad_perm:[1,0,3,2] row_mask:0xf bank_mask:0xf
	v_cndmask_b32_dpp v119, v171, v47, vcc quad_perm:[1,0,3,2] row_mask:0xf bank_mask:0xf
	s_mov_b64 vcc, s[62:63]
	v_cndmask_b32_dpp v168, v44, v168, vcc quad_perm:[1,0,3,2] row_mask:0xf bank_mask:0xf
	v_cndmask_b32_dpp v169, v45, v169, vcc quad_perm:[1,0,3,2] row_mask:0xf bank_mask:0xf
	v_cndmask_b32_dpp v170, v46, v170, vcc quad_perm:[1,0,3,2] row_mask:0xf bank_mask:0xf
	v_cndmask_b32_dpp v171, v47, v171, vcc quad_perm:[1,0,3,2] row_mask:0xf bank_mask:0xf
	global_store_dwordx4 v49, v[116:119], s[92:93]
	global_store_dwordx4 v49, v[168:171], s[92:93] offset:2048
	v_mov_b32_e32 v82, v173
	s_add_u32 s84, s30, 0x90000
	s_addc_u32 s85, s31, 0
	global_load_dwordx4 v[84:87], v209, s[84:85] offset:0
	global_load_dwordx4 v[88:91], v209, s[84:85] offset:16
	global_load_dwordx4 v[92:95], v209, s[84:85] offset:128
	global_load_dwordx4 v[116:119], v209, s[84:85] offset:144
	s_waitcnt vmcnt(10)
	v_pk_fma_f32 v[78:79], v[78:79], v[174:175], v[100:101]
	v_pk_fma_f32 v[80:81], v[80:81], v[176:177], v[102:103]
	v_pk_fma_f32 v[74:75], v[74:75], v[178:179], v[104:105]
	v_pk_fma_f32 v[76:77], v[76:77], v[180:181], v[106:107]
	v_pk_fma_f32 v[70:71], v[70:71], v[182:183], v[108:109]
	v_pk_fma_f32 v[72:73], v[72:73], v[184:185], v[110:111]
	v_pk_fma_f32 v[66:67], v[66:67], v[186:187], v[136:137]
	v_pk_fma_f32 v[68:69], v[68:69], v[188:189], v[138:139]
	v_mul_f32_e32 v28, v79, v79
	v_mul_f32_e32 v29, v81, v81
	v_mul_f32_e32 v30, v75, v75
	v_mul_f32_e32 v31, v77, v77
	v_fmac_f32_e32 v28, v78, v78
	v_fmac_f32_e32 v29, v80, v80
	v_fmac_f32_e32 v30, v74, v74
	v_fmac_f32_e32 v31, v76, v76
	v_add_f32_e32 v28, v28, v29
	v_add_f32_e32 v30, v30, v31
	v_add_f32_e32 v173, v28, v30
	v_add_u32_e32 v28, 0x80, v78
	v_add_u32_e32 v29, 0x80, v79
	v_add_u32_e32 v30, 0x80, v80
	v_add_u32_e32 v31, 0x80, v81
	v_perm_b32 v44, v29, v28, s78
	v_perm_b32 v45, v31, v30, s78
	v_perm_b32 v26, v29, v28, s79
	v_perm_b32 v27, v31, v30, s79
	v_perm_b32 v32, v27, v26, s60
	v_add_u32_e32 v28, 0x80, v74
	v_add_u32_e32 v29, 0x80, v75
	v_add_u32_e32 v30, 0x80, v76
	v_add_u32_e32 v31, 0x80, v77
	v_perm_b32 v46, v29, v28, s78
	v_perm_b32 v47, v31, v30, s78
	v_perm_b32 v26, v29, v28, s79
	v_perm_b32 v27, v31, v30, s79
	v_perm_b32 v33, v27, v26, s60
	v_mul_f32_e32 v28, v71, v71
	v_mul_f32_e32 v29, v73, v73
	v_mul_f32_e32 v30, v67, v67
	v_mul_f32_e32 v31, v69, v69
	v_fmac_f32_e32 v28, v70, v70
	v_fmac_f32_e32 v29, v72, v72
	v_fmac_f32_e32 v30, v66, v66
	v_fmac_f32_e32 v31, v68, v68
	v_add_f32_e32 v28, v28, v29
	v_add_f32_e32 v30, v30, v31
	v_add_f32_e32 v28, v28, v30
	v_add_f32_e32 v173, v173, v28
	v_add_u32_e32 v28, 0x80, v70
	v_add_u32_e32 v29, 0x80, v71
	v_add_u32_e32 v30, 0x80, v72
	v_add_u32_e32 v31, 0x80, v73
	v_perm_b32 v168, v29, v28, s78
	v_perm_b32 v169, v31, v30, s78
	v_perm_b32 v26, v29, v28, s79
	v_perm_b32 v27, v31, v30, s79
	v_perm_b32 v42, v27, v26, s60
	v_add_u32_e32 v28, 0x80, v66
	v_add_u32_e32 v29, 0x80, v67
	v_add_u32_e32 v30, 0x80, v68
	v_add_u32_e32 v31, 0x80, v69
	v_perm_b32 v170, v29, v28, s78
	v_perm_b32 v171, v31, v30, s78
	v_perm_b32 v26, v29, v28, s79
	v_perm_b32 v27, v31, v30, s79
	v_perm_b32 v43, v27, v26, s60
	s_mov_b64 vcc, s[66:67]
	v_cndmask_b32_dpp v100, v168, v44, vcc quad_perm:[1,0,3,2] row_mask:0xf bank_mask:0xf
	v_cndmask_b32_dpp v101, v169, v45, vcc quad_perm:[1,0,3,2] row_mask:0xf bank_mask:0xf
	v_cndmask_b32_dpp v102, v170, v46, vcc quad_perm:[1,0,3,2] row_mask:0xf bank_mask:0xf
	v_cndmask_b32_dpp v103, v171, v47, vcc quad_perm:[1,0,3,2] row_mask:0xf bank_mask:0xf
	s_mov_b64 vcc, s[62:63]
	v_cndmask_b32_dpp v168, v44, v168, vcc quad_perm:[1,0,3,2] row_mask:0xf bank_mask:0xf
	v_cndmask_b32_dpp v169, v45, v169, vcc quad_perm:[1,0,3,2] row_mask:0xf bank_mask:0xf
	v_cndmask_b32_dpp v170, v46, v170, vcc quad_perm:[1,0,3,2] row_mask:0xf bank_mask:0xf
	v_cndmask_b32_dpp v171, v47, v171, vcc quad_perm:[1,0,3,2] row_mask:0xf bank_mask:0xf
	s_mov_b64 vcc, s[66:67]
	v_cndmask_b32_dpp v104, v42, v32, vcc quad_perm:[1,0,3,2] row_mask:0xf bank_mask:0xf
	v_cndmask_b32_dpp v105, v43, v33, vcc quad_perm:[1,0,3,2] row_mask:0xf bank_mask:0xf
	s_mov_b64 vcc, s[62:63]
	v_cndmask_b32_dpp v42, v32, v42, vcc quad_perm:[1,0,3,2] row_mask:0xf bank_mask:0xf
	v_cndmask_b32_dpp v43, v33, v43, vcc quad_perm:[1,0,3,2] row_mask:0xf bank_mask:0xf
	s_add_u32 s88, s58, 0x40000
	s_addc_u32 s89, s59, 0
	s_add_u32 s90, s74, 0x20000
	s_addc_u32 s91, s75, 0
	global_store_dwordx4 v49, v[100:103], s[88:89]
	global_store_dwordx4 v49, v[168:171], s[88:89] offset:2048
	global_store_dwordx2 v48, v[104:105], s[90:91]
	global_store_dwordx2 v48, v[42:43], s[90:91] offset:1024
	s_add_u32 s92, s96, 0x40000
	s_addc_u32 s93, s97, 0
	v_pk_mul_f32 v[78:79], v[194:195], v[78:79]
	v_pk_mul_f32 v[80:81], v[196:197], v[80:81]
	v_pk_mul_f32 v[74:75], v[210:211], v[74:75]
	v_pk_mul_f32 v[76:77], v[212:213], v[76:77]
	v_cvt_pk_bf16_f32 v44, v78, v79
	v_cvt_pk_bf16_f32 v45, v80, v81
	v_cvt_pk_bf16_f32 v46, v74, v75
	v_cvt_pk_bf16_f32 v47, v76, v77
	v_pk_mul_f32 v[70:71], v[214:215], v[70:71]
	v_pk_mul_f32 v[72:73], v[216:217], v[72:73]
	v_pk_mul_f32 v[66:67], v[218:219], v[66:67]
	v_pk_mul_f32 v[68:69], v[220:221], v[68:69]
	v_cvt_pk_bf16_f32 v168, v70, v71
	v_cvt_pk_bf16_f32 v169, v72, v73
	v_cvt_pk_bf16_f32 v170, v66, v67
	v_cvt_pk_bf16_f32 v171, v68, v69
	s_mov_b64 vcc, s[66:67]
	v_cndmask_b32_dpp v100, v168, v44, vcc quad_perm:[1,0,3,2] row_mask:0xf bank_mask:0xf
	v_cndmask_b32_dpp v101, v169, v45, vcc quad_perm:[1,0,3,2] row_mask:0xf bank_mask:0xf
	v_cndmask_b32_dpp v102, v170, v46, vcc quad_perm:[1,0,3,2] row_mask:0xf bank_mask:0xf
	v_cndmask_b32_dpp v103, v171, v47, vcc quad_perm:[1,0,3,2] row_mask:0xf bank_mask:0xf
	s_mov_b64 vcc, s[62:63]
	v_cndmask_b32_dpp v168, v44, v168, vcc quad_perm:[1,0,3,2] row_mask:0xf bank_mask:0xf
	v_cndmask_b32_dpp v169, v45, v169, vcc quad_perm:[1,0,3,2] row_mask:0xf bank_mask:0xf
	v_cndmask_b32_dpp v170, v46, v170, vcc quad_perm:[1,0,3,2] row_mask:0xf bank_mask:0xf
	v_cndmask_b32_dpp v171, v47, v171, vcc quad_perm:[1,0,3,2] row_mask:0xf bank_mask:0xf
	global_store_dwordx4 v49, v[100:103], s[92:93]
	global_store_dwordx4 v49, v[168:171], s[92:93] offset:2048
	v_mov_b32_e32 v66, v173
	s_add_u32 s84, s30, 0xa0000
	s_addc_u32 s85, s31, 0
	global_load_dwordx4 v[68:71], v209, s[84:85] offset:0
	global_load_dwordx4 v[72:75], v209, s[84:85] offset:16
	global_load_dwordx4 v[76:79], v209, s[84:85] offset:128
	global_load_dwordx4 v[100:103], v209, s[84:85] offset:144
	s_waitcnt vmcnt(10)
	v_pk_fma_f32 v[62:63], v[62:63], v[174:175], v[84:85]
	v_pk_fma_f32 v[64:65], v[64:65], v[176:177], v[86:87]
	v_pk_fma_f32 v[58:59], v[58:59], v[178:179], v[88:89]
	v_pk_fma_f32 v[60:61], v[60:61], v[180:181], v[90:91]
	v_pk_fma_f32 v[54:55], v[54:55], v[182:183], v[92:93]
	v_pk_fma_f32 v[56:57], v[56:57], v[184:185], v[94:95]
	v_pk_fma_f32 v[50:51], v[50:51], v[186:187], v[116:117]
	v_pk_fma_f32 v[52:53], v[52:53], v[188:189], v[118:119]
	v_mul_f32_e32 v28, v63, v63
	v_mul_f32_e32 v29, v65, v65
	v_mul_f32_e32 v30, v59, v59
	v_mul_f32_e32 v31, v61, v61
	v_fmac_f32_e32 v28, v62, v62
	v_fmac_f32_e32 v29, v64, v64
	v_fmac_f32_e32 v30, v58, v58
	v_fmac_f32_e32 v31, v60, v60
	v_add_f32_e32 v28, v28, v29
	v_add_f32_e32 v30, v30, v31
	v_add_f32_e32 v173, v28, v30
	v_add_u32_e32 v28, 0x80, v62
	v_add_u32_e32 v29, 0x80, v63
	v_add_u32_e32 v30, 0x80, v64
	v_add_u32_e32 v31, 0x80, v65
	v_perm_b32 v44, v29, v28, s78
	v_perm_b32 v45, v31, v30, s78
	v_perm_b32 v26, v29, v28, s79
	v_perm_b32 v27, v31, v30, s79
	v_perm_b32 v32, v27, v26, s60
	v_add_u32_e32 v28, 0x80, v58
	v_add_u32_e32 v29, 0x80, v59
	v_add_u32_e32 v30, 0x80, v60
	v_add_u32_e32 v31, 0x80, v61
	v_perm_b32 v46, v29, v28, s78
	v_perm_b32 v47, v31, v30, s78
	v_perm_b32 v26, v29, v28, s79
	v_perm_b32 v27, v31, v30, s79
	v_perm_b32 v33, v27, v26, s60
	v_mul_f32_e32 v28, v55, v55
	v_mul_f32_e32 v29, v57, v57
	v_mul_f32_e32 v30, v51, v51
	v_mul_f32_e32 v31, v53, v53
	v_fmac_f32_e32 v28, v54, v54
	v_fmac_f32_e32 v29, v56, v56
	v_fmac_f32_e32 v30, v50, v50
	v_fmac_f32_e32 v31, v52, v52
	v_add_f32_e32 v28, v28, v29
	v_add_f32_e32 v30, v30, v31
	v_add_f32_e32 v28, v28, v30
	v_add_f32_e32 v173, v173, v28
	v_add_u32_e32 v28, 0x80, v54
	v_add_u32_e32 v29, 0x80, v55
	v_add_u32_e32 v30, 0x80, v56
	v_add_u32_e32 v31, 0x80, v57
	v_perm_b32 v168, v29, v28, s78
	v_perm_b32 v169, v31, v30, s78
	v_perm_b32 v26, v29, v28, s79
	v_perm_b32 v27, v31, v30, s79
	v_perm_b32 v42, v27, v26, s60
	v_add_u32_e32 v28, 0x80, v50
	v_add_u32_e32 v29, 0x80, v51
	v_add_u32_e32 v30, 0x80, v52
	v_add_u32_e32 v31, 0x80, v53
	v_perm_b32 v170, v29, v28, s78
	v_perm_b32 v171, v31, v30, s78
	v_perm_b32 v26, v29, v28, s79
	v_perm_b32 v27, v31, v30, s79
	v_perm_b32 v43, v27, v26, s60
	s_mov_b64 vcc, s[66:67]
	v_cndmask_b32_dpp v84, v168, v44, vcc quad_perm:[1,0,3,2] row_mask:0xf bank_mask:0xf
	v_cndmask_b32_dpp v85, v169, v45, vcc quad_perm:[1,0,3,2] row_mask:0xf bank_mask:0xf
	v_cndmask_b32_dpp v86, v170, v46, vcc quad_perm:[1,0,3,2] row_mask:0xf bank_mask:0xf
	v_cndmask_b32_dpp v87, v171, v47, vcc quad_perm:[1,0,3,2] row_mask:0xf bank_mask:0xf
	s_mov_b64 vcc, s[62:63]
	v_cndmask_b32_dpp v168, v44, v168, vcc quad_perm:[1,0,3,2] row_mask:0xf bank_mask:0xf
	v_cndmask_b32_dpp v169, v45, v169, vcc quad_perm:[1,0,3,2] row_mask:0xf bank_mask:0xf
	v_cndmask_b32_dpp v170, v46, v170, vcc quad_perm:[1,0,3,2] row_mask:0xf bank_mask:0xf
	v_cndmask_b32_dpp v171, v47, v171, vcc quad_perm:[1,0,3,2] row_mask:0xf bank_mask:0xf
	s_mov_b64 vcc, s[66:67]
	v_cndmask_b32_dpp v88, v42, v32, vcc quad_perm:[1,0,3,2] row_mask:0xf bank_mask:0xf
	v_cndmask_b32_dpp v89, v43, v33, vcc quad_perm:[1,0,3,2] row_mask:0xf bank_mask:0xf
	s_mov_b64 vcc, s[62:63]
	v_cndmask_b32_dpp v42, v32, v42, vcc quad_perm:[1,0,3,2] row_mask:0xf bank_mask:0xf
	v_cndmask_b32_dpp v43, v33, v43, vcc quad_perm:[1,0,3,2] row_mask:0xf bank_mask:0xf
	s_add_u32 s88, s58, 0x48000
	s_addc_u32 s89, s59, 0
	s_add_u32 s90, s74, 0x24000
	s_addc_u32 s91, s75, 0
	global_store_dwordx4 v49, v[84:87], s[88:89]
	global_store_dwordx4 v49, v[168:171], s[88:89] offset:2048
	global_store_dwordx2 v48, v[88:89], s[90:91]
	global_store_dwordx2 v48, v[42:43], s[90:91] offset:1024
	s_add_u32 s92, s96, 0x48000
	s_addc_u32 s93, s97, 0
	v_pk_mul_f32 v[62:63], v[194:195], v[62:63]
	v_pk_mul_f32 v[64:65], v[196:197], v[64:65]
	v_pk_mul_f32 v[58:59], v[210:211], v[58:59]
	v_pk_mul_f32 v[60:61], v[212:213], v[60:61]
	v_cvt_pk_bf16_f32 v44, v62, v63
	v_cvt_pk_bf16_f32 v45, v64, v65
	v_cvt_pk_bf16_f32 v46, v58, v59
	v_cvt_pk_bf16_f32 v47, v60, v61
	v_pk_mul_f32 v[54:55], v[214:215], v[54:55]
	v_pk_mul_f32 v[56:57], v[216:217], v[56:57]
	v_pk_mul_f32 v[50:51], v[218:219], v[50:51]
	v_pk_mul_f32 v[52:53], v[220:221], v[52:53]
	v_cvt_pk_bf16_f32 v168, v54, v55
	v_cvt_pk_bf16_f32 v169, v56, v57
	v_cvt_pk_bf16_f32 v170, v50, v51
	v_cvt_pk_bf16_f32 v171, v52, v53
	s_mov_b64 vcc, s[66:67]
	v_cndmask_b32_dpp v84, v168, v44, vcc quad_perm:[1,0,3,2] row_mask:0xf bank_mask:0xf
	v_cndmask_b32_dpp v85, v169, v45, vcc quad_perm:[1,0,3,2] row_mask:0xf bank_mask:0xf
	v_cndmask_b32_dpp v86, v170, v46, vcc quad_perm:[1,0,3,2] row_mask:0xf bank_mask:0xf
	v_cndmask_b32_dpp v87, v171, v47, vcc quad_perm:[1,0,3,2] row_mask:0xf bank_mask:0xf
	s_mov_b64 vcc, s[62:63]
	v_cndmask_b32_dpp v168, v44, v168, vcc quad_perm:[1,0,3,2] row_mask:0xf bank_mask:0xf
	v_cndmask_b32_dpp v169, v45, v169, vcc quad_perm:[1,0,3,2] row_mask:0xf bank_mask:0xf
	v_cndmask_b32_dpp v170, v46, v170, vcc quad_perm:[1,0,3,2] row_mask:0xf bank_mask:0xf
	v_cndmask_b32_dpp v171, v47, v171, vcc quad_perm:[1,0,3,2] row_mask:0xf bank_mask:0xf
	global_store_dwordx4 v49, v[84:87], s[92:93]
	global_store_dwordx4 v49, v[168:171], s[92:93] offset:2048
	v_mov_b32_e32 v50, v173
	s_add_u32 s84, s30, 0xb0000
	s_addc_u32 s85, s31, 0
	global_load_dwordx4 v[52:55], v209, s[84:85] offset:0
	global_load_dwordx4 v[56:59], v209, s[84:85] offset:16
	global_load_dwordx4 v[60:63], v209, s[84:85] offset:128
	global_load_dwordx4 v[84:87], v209, s[84:85] offset:144
	s_waitcnt vmcnt(10)
	v_pk_fma_f32 v[38:39], v[38:39], v[174:175], v[68:69]
	v_pk_fma_f32 v[40:41], v[40:41], v[176:177], v[70:71]
	v_pk_fma_f32 v[34:35], v[34:35], v[178:179], v[72:73]
	v_pk_fma_f32 v[36:37], v[36:37], v[180:181], v[74:75]
	v_pk_fma_f32 v[22:23], v[22:23], v[182:183], v[76:77]
	v_pk_fma_f32 v[24:25], v[24:25], v[184:185], v[78:79]
	v_pk_fma_f32 v[18:19], v[18:19], v[186:187], v[100:101]
	v_pk_fma_f32 v[20:21], v[20:21], v[188:189], v[102:103]
	v_mul_f32_e32 v28, v39, v39
	v_mul_f32_e32 v29, v41, v41
	v_mul_f32_e32 v30, v35, v35
	v_mul_f32_e32 v31, v37, v37
	v_fmac_f32_e32 v28, v38, v38
	v_fmac_f32_e32 v29, v40, v40
	v_fmac_f32_e32 v30, v34, v34
	v_fmac_f32_e32 v31, v36, v36
	v_add_f32_e32 v28, v28, v29
	v_add_f32_e32 v30, v30, v31
	v_add_f32_e32 v173, v28, v30
	v_add_u32_e32 v28, 0x80, v38
	v_add_u32_e32 v29, 0x80, v39
	v_add_u32_e32 v30, 0x80, v40
	v_add_u32_e32 v31, 0x80, v41
	v_perm_b32 v44, v29, v28, s78
	v_perm_b32 v45, v31, v30, s78
	v_perm_b32 v26, v29, v28, s79
	v_perm_b32 v27, v31, v30, s79
	v_perm_b32 v32, v27, v26, s60
	v_add_u32_e32 v28, 0x80, v34
	v_add_u32_e32 v29, 0x80, v35
	v_add_u32_e32 v30, 0x80, v36
	v_add_u32_e32 v31, 0x80, v37
	v_perm_b32 v46, v29, v28, s78
	v_perm_b32 v47, v31, v30, s78
	v_perm_b32 v26, v29, v28, s79
	v_perm_b32 v27, v31, v30, s79
	v_perm_b32 v33, v27, v26, s60
	v_mul_f32_e32 v28, v23, v23
	v_mul_f32_e32 v29, v25, v25
	v_mul_f32_e32 v30, v19, v19
	v_mul_f32_e32 v31, v21, v21
	v_fmac_f32_e32 v28, v22, v22
	v_fmac_f32_e32 v29, v24, v24
	v_fmac_f32_e32 v30, v18, v18
	v_fmac_f32_e32 v31, v20, v20
	v_add_f32_e32 v28, v28, v29
	v_add_f32_e32 v30, v30, v31
	v_add_f32_e32 v28, v28, v30
	v_add_f32_e32 v173, v173, v28
	v_add_u32_e32 v28, 0x80, v22
	v_add_u32_e32 v29, 0x80, v23
	v_add_u32_e32 v30, 0x80, v24
	v_add_u32_e32 v31, 0x80, v25
	v_perm_b32 v168, v29, v28, s78
	v_perm_b32 v169, v31, v30, s78
	v_perm_b32 v26, v29, v28, s79
	v_perm_b32 v27, v31, v30, s79
	v_perm_b32 v42, v27, v26, s60
	v_add_u32_e32 v28, 0x80, v18
	v_add_u32_e32 v29, 0x80, v19
	v_add_u32_e32 v30, 0x80, v20
	v_add_u32_e32 v31, 0x80, v21
	v_perm_b32 v170, v29, v28, s78
	v_perm_b32 v171, v31, v30, s78
	v_perm_b32 v26, v29, v28, s79
	v_perm_b32 v27, v31, v30, s79
	v_perm_b32 v43, v27, v26, s60
	s_mov_b64 vcc, s[66:67]
	v_cndmask_b32_dpp v68, v168, v44, vcc quad_perm:[1,0,3,2] row_mask:0xf bank_mask:0xf
	v_cndmask_b32_dpp v69, v169, v45, vcc quad_perm:[1,0,3,2] row_mask:0xf bank_mask:0xf
	v_cndmask_b32_dpp v70, v170, v46, vcc quad_perm:[1,0,3,2] row_mask:0xf bank_mask:0xf
	v_cndmask_b32_dpp v71, v171, v47, vcc quad_perm:[1,0,3,2] row_mask:0xf bank_mask:0xf
	s_mov_b64 vcc, s[62:63]
	v_cndmask_b32_dpp v168, v44, v168, vcc quad_perm:[1,0,3,2] row_mask:0xf bank_mask:0xf
	v_cndmask_b32_dpp v169, v45, v169, vcc quad_perm:[1,0,3,2] row_mask:0xf bank_mask:0xf
	v_cndmask_b32_dpp v170, v46, v170, vcc quad_perm:[1,0,3,2] row_mask:0xf bank_mask:0xf
	v_cndmask_b32_dpp v171, v47, v171, vcc quad_perm:[1,0,3,2] row_mask:0xf bank_mask:0xf
	s_mov_b64 vcc, s[66:67]
	v_cndmask_b32_dpp v72, v42, v32, vcc quad_perm:[1,0,3,2] row_mask:0xf bank_mask:0xf
	v_cndmask_b32_dpp v73, v43, v33, vcc quad_perm:[1,0,3,2] row_mask:0xf bank_mask:0xf
	s_mov_b64 vcc, s[62:63]
	v_cndmask_b32_dpp v42, v32, v42, vcc quad_perm:[1,0,3,2] row_mask:0xf bank_mask:0xf
	v_cndmask_b32_dpp v43, v33, v43, vcc quad_perm:[1,0,3,2] row_mask:0xf bank_mask:0xf
	s_add_u32 s88, s58, 0x50000
	s_addc_u32 s89, s59, 0
	s_add_u32 s90, s74, 0x28000
	s_addc_u32 s91, s75, 0
	global_store_dwordx4 v49, v[68:71], s[88:89]
	global_store_dwordx4 v49, v[168:171], s[88:89] offset:2048
	global_store_dwordx2 v48, v[72:73], s[90:91]
	global_store_dwordx2 v48, v[42:43], s[90:91] offset:1024
	s_add_u32 s92, s96, 0x50000
	s_addc_u32 s93, s97, 0
	v_pk_mul_f32 v[38:39], v[194:195], v[38:39]
	v_pk_mul_f32 v[40:41], v[196:197], v[40:41]
	v_pk_mul_f32 v[34:35], v[210:211], v[34:35]
	v_pk_mul_f32 v[36:37], v[212:213], v[36:37]
	v_cvt_pk_bf16_f32 v44, v38, v39
	v_cvt_pk_bf16_f32 v45, v40, v41
	v_cvt_pk_bf16_f32 v46, v34, v35
	v_cvt_pk_bf16_f32 v47, v36, v37
	v_pk_mul_f32 v[22:23], v[214:215], v[22:23]
	v_pk_mul_f32 v[24:25], v[216:217], v[24:25]
	v_pk_mul_f32 v[18:19], v[218:219], v[18:19]
	v_pk_mul_f32 v[20:21], v[220:221], v[20:21]
	v_cvt_pk_bf16_f32 v168, v22, v23
	v_cvt_pk_bf16_f32 v169, v24, v25
	v_cvt_pk_bf16_f32 v170, v18, v19
	v_cvt_pk_bf16_f32 v171, v20, v21
	s_mov_b64 vcc, s[66:67]
	v_cndmask_b32_dpp v68, v168, v44, vcc quad_perm:[1,0,3,2] row_mask:0xf bank_mask:0xf
	v_cndmask_b32_dpp v69, v169, v45, vcc quad_perm:[1,0,3,2] row_mask:0xf bank_mask:0xf
	v_cndmask_b32_dpp v70, v170, v46, vcc quad_perm:[1,0,3,2] row_mask:0xf bank_mask:0xf
	v_cndmask_b32_dpp v71, v171, v47, vcc quad_perm:[1,0,3,2] row_mask:0xf bank_mask:0xf
	s_mov_b64 vcc, s[62:63]
	v_cndmask_b32_dpp v168, v44, v168, vcc quad_perm:[1,0,3,2] row_mask:0xf bank_mask:0xf
	v_cndmask_b32_dpp v169, v45, v169, vcc quad_perm:[1,0,3,2] row_mask:0xf bank_mask:0xf
	v_cndmask_b32_dpp v170, v46, v170, vcc quad_perm:[1,0,3,2] row_mask:0xf bank_mask:0xf
	v_cndmask_b32_dpp v171, v47, v171, vcc quad_perm:[1,0,3,2] row_mask:0xf bank_mask:0xf
	global_store_dwordx4 v49, v[68:71], s[92:93]
	global_store_dwordx4 v49, v[168:171], s[92:93] offset:2048
	v_mov_b32_e32 v18, v173
	s_waitcnt vmcnt(6)
	v_pk_fma_f32 v[14:15], v[14:15], v[174:175], v[52:53]
	v_pk_fma_f32 v[16:17], v[16:17], v[176:177], v[54:55]
	v_pk_fma_f32 v[10:11], v[10:11], v[178:179], v[56:57]
	v_pk_fma_f32 v[12:13], v[12:13], v[180:181], v[58:59]
	v_pk_fma_f32 v[6:7], v[6:7], v[182:183], v[60:61]
	v_pk_fma_f32 v[8:9], v[8:9], v[184:185], v[62:63]
	v_pk_fma_f32 v[2:3], v[2:3], v[186:187], v[84:85]
	v_pk_fma_f32 v[4:5], v[4:5], v[188:189], v[86:87]
	v_mul_f32_e32 v28, v15, v15
	v_mul_f32_e32 v29, v17, v17
	v_mul_f32_e32 v30, v11, v11
	v_mul_f32_e32 v31, v13, v13
	v_fmac_f32_e32 v28, v14, v14
	v_fmac_f32_e32 v29, v16, v16
	v_fmac_f32_e32 v30, v10, v10
	v_fmac_f32_e32 v31, v12, v12
	v_add_f32_e32 v28, v28, v29
	v_add_f32_e32 v30, v30, v31
	v_add_f32_e32 v173, v28, v30
	v_add_u32_e32 v28, 0x80, v14
	v_add_u32_e32 v29, 0x80, v15
	v_add_u32_e32 v30, 0x80, v16
	v_add_u32_e32 v31, 0x80, v17
	v_perm_b32 v44, v29, v28, s78
	v_perm_b32 v45, v31, v30, s78
	v_perm_b32 v26, v29, v28, s79
	v_perm_b32 v27, v31, v30, s79
	v_perm_b32 v32, v27, v26, s60
	v_add_u32_e32 v28, 0x80, v10
	v_add_u32_e32 v29, 0x80, v11
	v_add_u32_e32 v30, 0x80, v12
	v_add_u32_e32 v31, 0x80, v13
	v_perm_b32 v46, v29, v28, s78
	v_perm_b32 v47, v31, v30, s78
	v_perm_b32 v26, v29, v28, s79
	v_perm_b32 v27, v31, v30, s79
	v_perm_b32 v33, v27, v26, s60
	v_mul_f32_e32 v28, v7, v7
	v_mul_f32_e32 v29, v9, v9
	v_mul_f32_e32 v30, v3, v3
	v_mul_f32_e32 v31, v5, v5
	v_fmac_f32_e32 v28, v6, v6
	v_fmac_f32_e32 v29, v8, v8
	v_fmac_f32_e32 v30, v2, v2
	v_fmac_f32_e32 v31, v4, v4
	v_add_f32_e32 v28, v28, v29
	v_add_f32_e32 v30, v30, v31
	v_add_f32_e32 v28, v28, v30
	v_add_f32_e32 v173, v173, v28
	v_add_u32_e32 v28, 0x80, v6
	v_add_u32_e32 v29, 0x80, v7
	v_add_u32_e32 v30, 0x80, v8
	v_add_u32_e32 v31, 0x80, v9
	v_perm_b32 v168, v29, v28, s78
	v_perm_b32 v169, v31, v30, s78
	v_perm_b32 v26, v29, v28, s79
	v_perm_b32 v27, v31, v30, s79
	v_perm_b32 v42, v27, v26, s60
	v_add_u32_e32 v28, 0x80, v2
	v_add_u32_e32 v29, 0x80, v3
	v_add_u32_e32 v30, 0x80, v4
	v_add_u32_e32 v31, 0x80, v5
	v_perm_b32 v170, v29, v28, s78
	v_perm_b32 v171, v31, v30, s78
	v_perm_b32 v26, v29, v28, s79
	v_perm_b32 v27, v31, v30, s79
	v_perm_b32 v43, v27, v26, s60
	s_mov_b64 vcc, s[66:67]
	v_cndmask_b32_dpp v52, v168, v44, vcc quad_perm:[1,0,3,2] row_mask:0xf bank_mask:0xf
	v_cndmask_b32_dpp v53, v169, v45, vcc quad_perm:[1,0,3,2] row_mask:0xf bank_mask:0xf
	v_cndmask_b32_dpp v54, v170, v46, vcc quad_perm:[1,0,3,2] row_mask:0xf bank_mask:0xf
	v_cndmask_b32_dpp v55, v171, v47, vcc quad_perm:[1,0,3,2] row_mask:0xf bank_mask:0xf
	s_mov_b64 vcc, s[62:63]
	v_cndmask_b32_dpp v168, v44, v168, vcc quad_perm:[1,0,3,2] row_mask:0xf bank_mask:0xf
	v_cndmask_b32_dpp v169, v45, v169, vcc quad_perm:[1,0,3,2] row_mask:0xf bank_mask:0xf
	v_cndmask_b32_dpp v170, v46, v170, vcc quad_perm:[1,0,3,2] row_mask:0xf bank_mask:0xf
	v_cndmask_b32_dpp v171, v47, v171, vcc quad_perm:[1,0,3,2] row_mask:0xf bank_mask:0xf
	s_mov_b64 vcc, s[66:67]
	v_cndmask_b32_dpp v56, v42, v32, vcc quad_perm:[1,0,3,2] row_mask:0xf bank_mask:0xf
	v_cndmask_b32_dpp v57, v43, v33, vcc quad_perm:[1,0,3,2] row_mask:0xf bank_mask:0xf
	s_mov_b64 vcc, s[62:63]
	v_cndmask_b32_dpp v42, v32, v42, vcc quad_perm:[1,0,3,2] row_mask:0xf bank_mask:0xf
	v_cndmask_b32_dpp v43, v33, v43, vcc quad_perm:[1,0,3,2] row_mask:0xf bank_mask:0xf
	s_add_u32 s88, s58, 0x58000
	s_addc_u32 s89, s59, 0
	s_add_u32 s90, s74, 0x2c000
	s_addc_u32 s91, s75, 0
	global_store_dwordx4 v49, v[52:55], s[88:89]
	global_store_dwordx4 v49, v[168:171], s[88:89] offset:2048
	global_store_dwordx2 v48, v[56:57], s[90:91]
	global_store_dwordx2 v48, v[42:43], s[90:91] offset:1024
	s_add_u32 s92, s96, 0x58000
	s_addc_u32 s93, s97, 0
	v_pk_mul_f32 v[14:15], v[194:195], v[14:15]
	v_pk_mul_f32 v[16:17], v[196:197], v[16:17]
	v_pk_mul_f32 v[10:11], v[210:211], v[10:11]
	v_pk_mul_f32 v[12:13], v[212:213], v[12:13]
	v_cvt_pk_bf16_f32 v44, v14, v15
	v_cvt_pk_bf16_f32 v45, v16, v17
	v_cvt_pk_bf16_f32 v46, v10, v11
	v_cvt_pk_bf16_f32 v47, v12, v13
	v_pk_mul_f32 v[6:7], v[214:215], v[6:7]
	v_pk_mul_f32 v[8:9], v[216:217], v[8:9]
	v_pk_mul_f32 v[2:3], v[218:219], v[2:3]
	v_pk_mul_f32 v[4:5], v[220:221], v[4:5]
	v_cvt_pk_bf16_f32 v168, v6, v7
	v_cvt_pk_bf16_f32 v169, v8, v9
	v_cvt_pk_bf16_f32 v170, v2, v3
	v_cvt_pk_bf16_f32 v171, v4, v5
	s_mov_b64 vcc, s[66:67]
	v_cndmask_b32_dpp v52, v168, v44, vcc quad_perm:[1,0,3,2] row_mask:0xf bank_mask:0xf
	v_cndmask_b32_dpp v53, v169, v45, vcc quad_perm:[1,0,3,2] row_mask:0xf bank_mask:0xf
	v_cndmask_b32_dpp v54, v170, v46, vcc quad_perm:[1,0,3,2] row_mask:0xf bank_mask:0xf
	v_cndmask_b32_dpp v55, v171, v47, vcc quad_perm:[1,0,3,2] row_mask:0xf bank_mask:0xf
	s_mov_b64 vcc, s[62:63]
	v_cndmask_b32_dpp v168, v44, v168, vcc quad_perm:[1,0,3,2] row_mask:0xf bank_mask:0xf
	v_cndmask_b32_dpp v169, v45, v169, vcc quad_perm:[1,0,3,2] row_mask:0xf bank_mask:0xf
	v_cndmask_b32_dpp v170, v46, v170, vcc quad_perm:[1,0,3,2] row_mask:0xf bank_mask:0xf
	v_cndmask_b32_dpp v171, v47, v171, vcc quad_perm:[1,0,3,2] row_mask:0xf bank_mask:0xf
	global_store_dwordx4 v49, v[52:55], s[92:93]
	global_store_dwordx4 v49, v[168:171], s[92:93] offset:2048
	v_mov_b32_e32 v2, v173
	v_mbcnt_lo_u32_b32 v3, -1, 0
	v_mbcnt_hi_u32_b32 v3, -1, v3
	v_xor_b32_e32 v4, 16, v3
	v_xor_b32_e32 v5, 32, v3
	v_lshlrev_b32_e32 v4, 2, v4
	v_lshlrev_b32_e32 v5, 2, v5
	v_cmp_gt_u32_e64 s[54:55], 16, v3
	ds_bpermute_b32 v6, v4, v130
	ds_bpermute_b32 v7, v4, v114
	ds_bpermute_b32 v8, v4, v98
	ds_bpermute_b32 v9, v4, v82
	ds_bpermute_b32 v10, v4, v66
	ds_bpermute_b32 v11, v4, v50
	ds_bpermute_b32 v12, v4, v18
	ds_bpermute_b32 v13, v4, v2
	s_waitcnt lgkmcnt(0)
	v_add_f32_e32 v130, v130, v6
	v_add_f32_e32 v114, v114, v7
	v_add_f32_e32 v98, v98, v8
	v_add_f32_e32 v82, v82, v9
	v_add_f32_e32 v66, v66, v10
	v_add_f32_e32 v50, v50, v11
	v_add_f32_e32 v18, v18, v12
	v_add_f32_e32 v2, v2, v13
	ds_bpermute_b32 v6, v5, v130
	ds_bpermute_b32 v7, v5, v114
	ds_bpermute_b32 v8, v5, v98
	ds_bpermute_b32 v9, v5, v82
	ds_bpermute_b32 v10, v5, v66
	ds_bpermute_b32 v11, v5, v50
	ds_bpermute_b32 v12, v5, v18
	ds_bpermute_b32 v13, v5, v2
	s_waitcnt lgkmcnt(0)
	v_add_f32_e32 v130, v130, v6
	v_add_f32_e32 v114, v114, v7
	v_add_f32_e32 v98, v98, v8
	v_add_f32_e32 v82, v82, v9
	v_add_f32_e32 v66, v66, v10
	v_add_f32_e32 v50, v50, v11
	v_add_f32_e32 v18, v18, v12
	v_add_f32_e32 v2, v2, v13
	v_readlane_b32 s70, v244, 53
	v_readlane_b32 s71, v244, 54
	v_lshlrev_b32_e32 v3, 6, v190
	s_lshl_b32 s94, s53, 14
	s_lshl_b32 s95, s4, 4
	s_add_u32 s94, s94, s95
	s_lshl_b32 s95, s47, 2
	s_add_u32 s94, s94, s95
	s_add_u32 s94, s70, s94
	s_addc_u32 s95, s71, 0
	s_and_saveexec_b64 s[56:57], s[54:55]
	global_store_dword v3, v130, s[94:95]
	s_add_u32 s84, s94, 0x400
	s_addc_u32 s85, s95, 0
	global_store_dword v3, v114, s[84:85]
	s_add_u32 s84, s94, 0x800
	s_addc_u32 s85, s95, 0
	global_store_dword v3, v98, s[84:85]
	s_add_u32 s84, s94, 0xc00
	s_addc_u32 s85, s95, 0
	global_store_dword v3, v82, s[84:85]
	s_add_u32 s84, s94, 0x2000
	s_addc_u32 s85, s95, 0
	global_store_dword v3, v66, s[84:85]
	s_add_u32 s84, s94, 0x2400
	s_addc_u32 s85, s95, 0
	global_store_dword v3, v50, s[84:85]
	s_add_u32 s84, s94, 0x2800
	s_addc_u32 s85, s95, 0
	global_store_dword v3, v18, s[84:85]
	s_add_u32 s84, s94, 0x2c00
	s_addc_u32 s85, s95, 0
	global_store_dword v3, v2, s[84:85]
	s_or_b64 exec, exec, s[56:57]
	v_readlane_b32 s56, v246, 3
	v_readlane_b32 s57, v246, 4
	s_andn2_b64 vcc, exec, s[18:19]
	s_mov_b64 s[12:13], -1
	s_cbranch_vccnz .LBB0_1218
	s_andn2_b64 vcc, exec, s[0:1]
	s_cbranch_vccnz .LBB0_1217
	s_barrier
	s_branch .LBB0_1217
